# SwiGLU GEMM K-loop: LDS-DMA loads use SGPR base + 32-bit VGPR offset, no per-load 64-bit VALU address add
# speedup vs baseline: 1.0054x; 1.0054x over previous
.LBB0_251:
	s_ashr_i32 s13, s12, 31
	s_lshl_b64 s[14:15], s[12:13], 19
	s_add_u32 s14, s29, s14
	s_addc_u32 s15, s38, s15
	s_and_b64 s[16:17], s[4:5], exec
	s_cselect_b32 s13, s15, s23
	s_cselect_b32 s19, s14, s22
	s_ashr_i32 s11, s10, 31
	s_lshl_b64 s[16:17], s[10:11], 19
	s_add_u32 s16, s39, s16
	s_addc_u32 s17, s40, s17
	s_and_b64 s[24:25], s[4:5], exec
	s_cselect_b32 s11, s17, s21
	s_cselect_b32 s61, s16, s20
	s_add_u32 s62, s20, 0x100
	s_addc_u32 s63, s21, 0
	s_add_u32 s20, s22, 0x40080
	s_addc_u32 s21, s23, 0
	s_mov_b32 s68, -2
	s_add_u32 s22, s20, 0xfffc0080
	s_addc_u32 s23, s21, -1
	s_add_i32 s64, 0, 0x10000
	s_cmp_eq_u32 s68, 12
	s_cselect_b32 s25, s13, s23
	s_cselect_b32 s24, s19, s22
	s_cselect_b32 s23, s11, s63
	s_cselect_b32 s22, s61, s62
	s_lshl_b32 s74, s18, 8
	v_add_u32_e32 v178, s74, v168
	v_ashrrev_i32_e32 v179, 31, v178
	v_lshlrev_b64 v[178:179], 6, v[178:179]
	v_lshl_add_u64 v[178:179], s[70:71], 0, v[178:179]
	s_and_saveexec_b64 s[78:79], s[2:3]
	global_load_dwordx4 v[238:241], v[178:179], off
	global_load_dwordx4 v[242:245], v[178:179], off offset:16
	global_load_dwordx4 v[246:249], v[178:179], off offset:32
	global_load_dwordx4 v[250:253], v[178:179], off offset:48
	s_mov_b64 exec, s[78:79]
	s_add_i32 s69, 0, 0x14000
	v_add_u32_e32 v140, s64, v167
	v_add_u32_e32 v164, s69, v167
	ds_read_b128 v[48:51], v140
	ds_read_b128 v[56:59], v140 offset:1024
	ds_read_b128 v[136:139], v140 offset:2048
	ds_read_b128 v[140:143], v140 offset:3072
	ds_read_b128 v[156:159], v164
	ds_read_b128 v[160:163], v164 offset:1024
	ds_read_b128 v[182:185], v164 offset:2048
	ds_read_b128 v[186:189], v164 offset:3072
	s_add_i32 m0, s49, 0xc000
	ds_read_b128 v[190:193], v172
	ds_read_b128 v[194:197], v172 offset:1024
	ds_read_b128 v[198:201], v172 offset:2048
	ds_read_b128 v[202:205], v172 offset:3072
	ds_read_b128 v[206:209], v172 offset:4096
	ds_read_b128 v[210:213], v172 offset:5120
	ds_read_b128 v[228:231], v172 offset:6144
	ds_read_b128 v[232:235], v172 offset:7168
	global_load_lds_dwordx4 v154, s[20:21]
	s_add_i32 m0, s49, 0xe000
	s_nop 0
	global_load_lds_dwordx4 v152, s[20:21]
	s_waitcnt vmcnt(12)
	s_waitcnt lgkmcnt(0)
	s_barrier
	s_setprio 1
	v_mfma_f32_16x16x32_bf16 v[132:135], v[48:51], v[190:193], 0
	v_mfma_f32_16x16x32_bf16 v[124:127], v[136:139], v[190:193], 0
	v_mfma_f32_16x16x32_bf16 v[116:119], v[48:51], v[198:201], 0
	v_mfma_f32_16x16x32_bf16 v[112:115], v[136:139], v[198:201], 0
	v_mfma_f32_16x16x32_bf16 v[100:103], v[48:51], v[206:209], 0
	v_mfma_f32_16x16x32_bf16 v[96:99], v[136:139], v[206:209], 0
	v_mfma_f32_16x16x32_bf16 v[84:87], v[48:51], v[228:231], 0
	v_mfma_f32_16x16x32_bf16 v[80:83], v[136:139], v[228:231], 0
	v_mfma_f32_16x16x32_bf16 v[132:135], v[56:59], v[194:197], v[132:135]
	v_mfma_f32_16x16x32_bf16 v[124:127], v[140:143], v[194:197], v[124:127]
	v_mfma_f32_16x16x32_bf16 v[116:119], v[56:59], v[202:205], v[116:119]
	v_mfma_f32_16x16x32_bf16 v[112:115], v[140:143], v[202:205], v[112:115]
	v_mfma_f32_16x16x32_bf16 v[100:103], v[56:59], v[210:213], v[100:103]
	v_mfma_f32_16x16x32_bf16 v[96:99], v[140:143], v[210:213], v[96:99]
	v_mfma_f32_16x16x32_bf16 v[84:87], v[56:59], v[232:235], v[84:87]
	v_mfma_f32_16x16x32_bf16 v[80:83], v[140:143], v[232:235], v[80:83]
	v_mfma_f32_16x16x32_bf16 v[128:131], v[156:159], v[190:193], 0
	v_mfma_f32_16x16x32_bf16 v[120:123], v[182:185], v[190:193], 0
	v_mfma_f32_16x16x32_bf16 v[108:111], v[156:159], v[198:201], 0
	v_mfma_f32_16x16x32_bf16 v[104:107], v[182:185], v[198:201], 0
	v_mfma_f32_16x16x32_bf16 v[92:95], v[156:159], v[206:209], 0
	v_mfma_f32_16x16x32_bf16 v[88:91], v[182:185], v[206:209], 0
	v_mfma_f32_16x16x32_bf16 v[76:79], v[156:159], v[228:231], 0
	v_mfma_f32_16x16x32_bf16 v[72:75], v[182:185], v[228:231], 0
	v_mfma_f32_16x16x32_bf16 v[128:131], v[160:163], v[194:197], v[128:131]
	v_mfma_f32_16x16x32_bf16 v[120:123], v[186:189], v[194:197], v[120:123]
	v_mfma_f32_16x16x32_bf16 v[108:111], v[160:163], v[202:205], v[108:111]
	v_mfma_f32_16x16x32_bf16 v[104:107], v[186:189], v[202:205], v[104:107]
	s_setprio 2
	s_barrier
	v_mfma_f32_16x16x32_bf16 v[92:95], v[160:163], v[210:213], v[92:95]
	v_mfma_f32_16x16x32_bf16 v[88:91], v[186:189], v[210:213], v[88:91]
	v_mfma_f32_16x16x32_bf16 v[76:79], v[160:163], v[232:235], v[76:79]
	v_mfma_f32_16x16x32_bf16 v[72:75], v[186:189], v[232:235], v[72:75]
	s_setprio 0
	s_add_i32 s64, s64, s41
	s_add_u32 s94, s22, s34
	s_addc_u32 s95, s23, s35
	s_mov_b32 m0, s64
	ds_read_b128 v[190:193], v172 offset:16384
	ds_read_b128 v[194:197], v172 offset:17408
	ds_read_b128 v[198:201], v172 offset:18432
	ds_read_b128 v[202:205], v172 offset:19456
	ds_read_b128 v[206:209], v172 offset:20480
	ds_read_b128 v[210:213], v172 offset:21504
	ds_read_b128 v[228:231], v172 offset:22528
	ds_read_b128 v[232:235], v172 offset:23552
	global_load_lds_dwordx4 v148, s[22:23]
	s_add_i32 m0, s64, 0x2000
	s_add_u32 s64, s22, 0x40000
	s_addc_u32 s65, s23, 0
	s_add_i32 s69, s69, s41
	global_load_lds_dwordx4 v144, s[22:23]
	s_mov_b32 m0, s69
	s_nop 0
	global_load_lds_dwordx4 v148, s[64:65]
	s_add_i32 m0, s69, 0x2000
	s_nop 0
	global_load_lds_dwordx4 v144, s[64:65]
	s_add_u32 s98, s24, s34
	s_addc_u32 s99, s25, s35
	s_mov_b32 m0, s49
	s_nop 0
	global_load_lds_dwordx4 v150, s[24:25]
	s_mov_b32 m0, s50
	s_nop 0
	global_load_lds_dwordx4 v146, s[24:25]
	s_waitcnt vmcnt(8)
	s_waitcnt lgkmcnt(0)
	s_barrier
	s_setprio 1
	v_mfma_f32_16x16x32_bf16 v[68:71], v[48:51], v[190:193], 0
	v_mfma_f32_16x16x32_bf16 v[64:67], v[136:139], v[190:193], 0
	v_mfma_f32_16x16x32_bf16 v[44:47], v[48:51], v[198:201], 0
	v_mfma_f32_16x16x32_bf16 v[40:43], v[136:139], v[198:201], 0
	v_mfma_f32_16x16x32_bf16 v[28:31], v[48:51], v[206:209], 0
	v_mfma_f32_16x16x32_bf16 v[24:27], v[136:139], v[206:209], 0
	v_mfma_f32_16x16x32_bf16 v[12:15], v[48:51], v[228:231], 0
	v_mfma_f32_16x16x32_bf16 v[8:11], v[136:139], v[228:231], 0
	v_mfma_f32_16x16x32_bf16 v[68:71], v[56:59], v[194:197], v[68:71]
	v_mfma_f32_16x16x32_bf16 v[64:67], v[140:143], v[194:197], v[64:67]
	v_mfma_f32_16x16x32_bf16 v[44:47], v[56:59], v[202:205], v[44:47]
	v_mfma_f32_16x16x32_bf16 v[40:43], v[140:143], v[202:205], v[40:43]
	v_mfma_f32_16x16x32_bf16 v[28:31], v[56:59], v[210:213], v[28:31]
	v_mfma_f32_16x16x32_bf16 v[24:27], v[140:143], v[210:213], v[24:27]
	v_mfma_f32_16x16x32_bf16 v[12:15], v[56:59], v[232:235], v[12:15]
	v_mfma_f32_16x16x32_bf16 v[8:11], v[140:143], v[232:235], v[8:11]
	v_mfma_f32_16x16x32_bf16 v[52:55], v[182:185], v[190:193], 0
	v_mfma_f32_16x16x32_bf16 v[36:39], v[156:159], v[198:201], 0
	v_mfma_f32_16x16x32_bf16 v[32:35], v[182:185], v[198:201], 0
	v_mfma_f32_16x16x32_bf16 v[20:23], v[156:159], v[206:209], 0
	v_mfma_f32_16x16x32_bf16 v[16:19], v[182:185], v[206:209], 0
	v_mfma_f32_16x16x32_bf16 v[4:7], v[156:159], v[228:231], 0
	v_mfma_f32_16x16x32_bf16 v[0:3], v[182:185], v[228:231], 0
	v_mfma_f32_16x16x32_bf16 v[48:51], v[156:159], v[190:193], 0
	v_mfma_f32_16x16x32_bf16 v[52:55], v[186:189], v[194:197], v[52:55]
	v_mfma_f32_16x16x32_bf16 v[36:39], v[160:163], v[202:205], v[36:39]
	v_mfma_f32_16x16x32_bf16 v[32:35], v[186:189], v[202:205], v[32:35]
	v_mfma_f32_16x16x32_bf16 v[20:23], v[160:163], v[210:213], v[20:23]
	s_setprio 2
	s_barrier
	v_mfma_f32_16x16x32_bf16 v[16:19], v[186:189], v[210:213], v[16:19]
	v_mfma_f32_16x16x32_bf16 v[4:7], v[160:163], v[232:235], v[4:7]
	v_mfma_f32_16x16x32_bf16 v[0:3], v[186:189], v[232:235], v[0:3]
	v_mfma_f32_16x16x32_bf16 v[48:51], v[160:163], v[194:197], v[48:51]
	s_setprio 0
	s_and_saveexec_b64 s[78:79], s[2:3]
	v_add_f32_e32 v238, v238, v239
	v_add_f32_e32 v240, v240, v241
	v_add_f32_e32 v242, v242, v243
	v_add_f32_e32 v244, v244, v245
	v_add_f32_e32 v246, v246, v247
	v_add_f32_e32 v248, v248, v249
	v_add_f32_e32 v250, v250, v251
	v_add_f32_e32 v252, v252, v253
	v_add_f32_e32 v238, v238, v240
	v_add_f32_e32 v242, v242, v244
	v_add_f32_e32 v246, v246, v248
	v_add_f32_e32 v250, v250, v252
	v_add_f32_e32 v238, v238, v242
	v_add_f32_e32 v246, v246, v250
	v_add_f32_e32 v238, v238, v246
	v_fmamk_f32 v238, v238, 0x3a800000, v216
	v_rsq_f32_e32 v238, v238
	s_nop 0
	ds_write_b32 v169, v238
	s_mov_b64 exec, s[78:79]
	s_add_i32 s64, 0, 0x18000
	s_add_i32 s65, 0, 0x1c000
	v_add_u32_e32 v140, s64, v167
	v_add_u32_e32 v173, s65, v167
	ds_read_b128 v[56:59], v140
	ds_read_b128 v[60:63], v140 offset:1024
	ds_read_b128 v[136:139], v140 offset:2048
	ds_read_b128 v[140:143], v140 offset:3072
	ds_read_b128 v[156:159], v173
	ds_read_b128 v[160:163], v173 offset:1024
	ds_read_b128 v[182:185], v173 offset:2048
	ds_read_b128 v[186:189], v173 offset:3072
	s_add_u32 s24, s24, 0x40000
	s_addc_u32 s25, s25, 0
	s_mov_b32 m0, s51
	ds_read_b128 v[190:193], v172 offset:32768
	ds_read_b128 v[194:197], v172 offset:33792
	ds_read_b128 v[198:201], v172 offset:34816
	ds_read_b128 v[202:205], v172 offset:35840
	ds_read_b128 v[206:209], v172 offset:36864
	ds_read_b128 v[210:213], v172 offset:37888
	ds_read_b128 v[228:231], v172 offset:38912
	ds_read_b128 v[232:235], v172 offset:39936
	global_load_lds_dwordx4 v150, s[24:25]
	s_mov_b32 m0, s52
	s_nop 0
	global_load_lds_dwordx4 v146, s[24:25]
	s_waitcnt vmcnt(8)
	s_waitcnt lgkmcnt(0)
	s_barrier
	s_setprio 1
	v_mfma_f32_16x16x32_bf16 v[132:135], v[56:59], v[190:193], v[132:135]
	v_mfma_f32_16x16x32_bf16 v[124:127], v[136:139], v[190:193], v[124:127]
	v_mfma_f32_16x16x32_bf16 v[116:119], v[56:59], v[198:201], v[116:119]
	v_mfma_f32_16x16x32_bf16 v[112:115], v[136:139], v[198:201], v[112:115]
	v_mfma_f32_16x16x32_bf16 v[100:103], v[56:59], v[206:209], v[100:103]
	v_mfma_f32_16x16x32_bf16 v[96:99], v[136:139], v[206:209], v[96:99]
	v_mfma_f32_16x16x32_bf16 v[84:87], v[56:59], v[228:231], v[84:87]
	v_mfma_f32_16x16x32_bf16 v[80:83], v[136:139], v[228:231], v[80:83]
	v_mfma_f32_16x16x32_bf16 v[132:135], v[60:63], v[194:197], v[132:135]
	v_mfma_f32_16x16x32_bf16 v[124:127], v[140:143], v[194:197], v[124:127]
	v_mfma_f32_16x16x32_bf16 v[116:119], v[60:63], v[202:205], v[116:119]
	v_mfma_f32_16x16x32_bf16 v[112:115], v[140:143], v[202:205], v[112:115]
	v_mfma_f32_16x16x32_bf16 v[100:103], v[60:63], v[210:213], v[100:103]
	v_mfma_f32_16x16x32_bf16 v[96:99], v[140:143], v[210:213], v[96:99]
	v_mfma_f32_16x16x32_bf16 v[84:87], v[60:63], v[232:235], v[84:87]
	v_mfma_f32_16x16x32_bf16 v[80:83], v[140:143], v[232:235], v[80:83]
	v_mfma_f32_16x16x32_bf16 v[128:131], v[156:159], v[190:193], v[128:131]
	v_mfma_f32_16x16x32_bf16 v[120:123], v[182:185], v[190:193], v[120:123]
	v_mfma_f32_16x16x32_bf16 v[108:111], v[156:159], v[198:201], v[108:111]
	v_mfma_f32_16x16x32_bf16 v[104:107], v[182:185], v[198:201], v[104:107]
	v_mfma_f32_16x16x32_bf16 v[92:95], v[156:159], v[206:209], v[92:95]
	v_mfma_f32_16x16x32_bf16 v[88:91], v[182:185], v[206:209], v[88:91]
	v_mfma_f32_16x16x32_bf16 v[76:79], v[156:159], v[228:231], v[76:79]
	v_mfma_f32_16x16x32_bf16 v[72:75], v[182:185], v[228:231], v[72:75]
	v_mfma_f32_16x16x32_bf16 v[128:131], v[160:163], v[194:197], v[128:131]
	v_mfma_f32_16x16x32_bf16 v[120:123], v[186:189], v[194:197], v[120:123]
	v_mfma_f32_16x16x32_bf16 v[108:111], v[160:163], v[202:205], v[108:111]
	v_mfma_f32_16x16x32_bf16 v[104:107], v[186:189], v[202:205], v[104:107]
	s_setprio 2
	s_barrier
	v_mfma_f32_16x16x32_bf16 v[92:95], v[160:163], v[210:213], v[92:95]
	v_mfma_f32_16x16x32_bf16 v[88:91], v[186:189], v[210:213], v[88:91]
	v_mfma_f32_16x16x32_bf16 v[76:79], v[160:163], v[232:235], v[76:79]
	v_mfma_f32_16x16x32_bf16 v[72:75], v[186:189], v[232:235], v[72:75]
	s_setprio 0
	s_min_i32 s74, s18, 0x80
	s_ashr_i32 s74, s74, 3
	s_mul_hi_i32 s75, s74, 0x5800
	s_mulk_i32 s74, 0x5800
	s_add_u32 s74, s53, s74
	s_addc_u32 s75, s54, s75
	s_lshl_b32 s76, s60, 8
	s_ashr_i32 s77, s76, 31
	s_lshl_b64 s[76:77], s[76:77], 2
	s_add_u32 s74, s74, s76
	s_addc_u32 s75, s75, s77
	s_add_u32 s74, s74, s59
	s_addc_u32 s75, s75, 0
	v_lshl_add_u64 v[178:179], s[74:75], 0, v[176:177]
	global_load_dwordx4 v[238:241], v[178:179], off
	global_load_dwordx4 v[242:245], v[178:179], off offset:16
	global_load_dwordx4 v[246:249], v[178:179], off offset:512
	global_load_dwordx4 v[250:253], v[178:179], off offset:528
	s_add_i32 s24, s64, s41
	s_mov_b32 m0, s24
	ds_read_b128 v[190:193], v172 offset:49152
	ds_read_b128 v[194:197], v172 offset:50176
	ds_read_b128 v[198:201], v172 offset:51200
	ds_read_b128 v[202:205], v172 offset:52224
	ds_read_b128 v[206:209], v172 offset:53248
	ds_read_b128 v[210:213], v172 offset:54272
	ds_read_b128 v[228:231], v172 offset:55296
	ds_read_b128 v[232:235], v172 offset:56320
	global_load_lds_dwordx4 v148, s[94:95]
	s_add_i32 m0, s24, 0x2000
	s_add_u32 s22, s22, 0x40080
	s_addc_u32 s23, s23, 0
	s_add_i32 s24, s65, s41
	global_load_lds_dwordx4 v144, s[94:95]
	s_mov_b32 m0, s24
	s_nop 0
	global_load_lds_dwordx4 v148, s[22:23]
	s_add_i32 m0, s24, 0x2000
	s_nop 0
	global_load_lds_dwordx4 v144, s[22:23]
	s_mov_b32 m0, s55
	s_nop 0
	global_load_lds_dwordx4 v150, s[98:99]
	s_mov_b32 m0, s56
	s_nop 0
	global_load_lds_dwordx4 v146, s[98:99]
	s_waitcnt vmcnt(12)
	s_waitcnt lgkmcnt(0)
	s_barrier
	s_setprio 1
	v_mfma_f32_16x16x32_bf16 v[68:71], v[56:59], v[190:193], v[68:71]
	v_mfma_f32_16x16x32_bf16 v[64:67], v[136:139], v[190:193], v[64:67]
	v_mfma_f32_16x16x32_bf16 v[44:47], v[56:59], v[198:201], v[44:47]
	v_mfma_f32_16x16x32_bf16 v[40:43], v[136:139], v[198:201], v[40:43]
	v_mfma_f32_16x16x32_bf16 v[28:31], v[56:59], v[206:209], v[28:31]
	v_mfma_f32_16x16x32_bf16 v[24:27], v[136:139], v[206:209], v[24:27]
	v_mfma_f32_16x16x32_bf16 v[12:15], v[56:59], v[228:231], v[12:15]
	v_mfma_f32_16x16x32_bf16 v[8:11], v[136:139], v[228:231], v[8:11]
	v_mfma_f32_16x16x32_bf16 v[68:71], v[60:63], v[194:197], v[68:71]
	v_mfma_f32_16x16x32_bf16 v[64:67], v[140:143], v[194:197], v[64:67]
	v_mfma_f32_16x16x32_bf16 v[44:47], v[60:63], v[202:205], v[44:47]
	v_mfma_f32_16x16x32_bf16 v[40:43], v[140:143], v[202:205], v[40:43]
	v_mfma_f32_16x16x32_bf16 v[28:31], v[60:63], v[210:213], v[28:31]
	v_mfma_f32_16x16x32_bf16 v[24:27], v[140:143], v[210:213], v[24:27]
	v_mfma_f32_16x16x32_bf16 v[12:15], v[60:63], v[232:235], v[12:15]
	v_mfma_f32_16x16x32_bf16 v[8:11], v[140:143], v[232:235], v[8:11]
	v_mfma_f32_16x16x32_bf16 v[48:51], v[156:159], v[190:193], v[48:51]
	v_mfma_f32_16x16x32_bf16 v[60:63], v[160:163], v[194:197], v[48:51]
	v_mfma_f32_16x16x32_bf16 v[48:51], v[182:185], v[190:193], v[52:55]
	v_mfma_f32_16x16x32_bf16 v[36:39], v[156:159], v[198:201], v[36:39]
	v_mfma_f32_16x16x32_bf16 v[32:35], v[182:185], v[198:201], v[32:35]
	v_mfma_f32_16x16x32_bf16 v[20:23], v[156:159], v[206:209], v[20:23]
	v_mfma_f32_16x16x32_bf16 v[16:19], v[182:185], v[206:209], v[16:19]
	v_mfma_f32_16x16x32_bf16 v[4:7], v[156:159], v[228:231], v[4:7]
	v_mfma_f32_16x16x32_bf16 v[0:3], v[182:185], v[228:231], v[0:3]
	v_mfma_f32_16x16x32_bf16 v[52:55], v[186:189], v[194:197], v[48:51]
	v_mfma_f32_16x16x32_bf16 v[36:39], v[160:163], v[202:205], v[36:39]
	v_mfma_f32_16x16x32_bf16 v[32:35], v[186:189], v[202:205], v[32:35]
	s_setprio 2
	s_barrier
	v_mfma_f32_16x16x32_bf16 v[20:23], v[160:163], v[210:213], v[20:23]
	v_mfma_f32_16x16x32_bf16 v[16:19], v[186:189], v[210:213], v[16:19]
	v_mfma_f32_16x16x32_bf16 v[4:7], v[160:163], v[232:235], v[4:7]
	v_mfma_f32_16x16x32_bf16 v[0:3], v[186:189], v[232:235], v[0:3]
	s_setprio 0
	s_add_i32 s68, s68, 2
	s_add_u32 s62, s62, 0x100
	s_addc_u32 s63, s63, 0
	s_add_u32 s20, s20, 0x100
	s_addc_u32 s21, s21, 0
	s_cmp_gt_u32 s68, 13
.LBB0_252:
	s_add_u32 s22, s20, 0xfffc0080
	s_addc_u32 s23, s21, -1
	s_add_i32 s64, 0, 0x10000
	s_cmp_eq_u32 s68, 12
	s_cselect_b32 s25, s13, s23
	s_cselect_b32 s24, s19, s22
	s_cselect_b32 s23, s11, s63
	s_cselect_b32 s22, s61, s62
	s_add_i32 s69, 0, 0x14000
	v_add_u32_e32 v140, s64, v167
	v_add_u32_e32 v164, s69, v167
	ds_read_b128 v[48:51], v140
	ds_read_b128 v[56:59], v140 offset:1024
	ds_read_b128 v[136:139], v140 offset:2048
	ds_read_b128 v[140:143], v140 offset:3072
	ds_read_b128 v[156:159], v164
	ds_read_b128 v[160:163], v164 offset:1024
	ds_read_b128 v[182:185], v164 offset:2048
	ds_read_b128 v[186:189], v164 offset:3072
	s_add_i32 m0, s49, 0xc000
	ds_read_b128 v[190:193], v172
	ds_read_b128 v[194:197], v172 offset:1024
	ds_read_b128 v[198:201], v172 offset:2048
	ds_read_b128 v[202:205], v172 offset:3072
	ds_read_b128 v[206:209], v172 offset:4096
	ds_read_b128 v[210:213], v172 offset:5120
	ds_read_b128 v[228:231], v172 offset:6144
	ds_read_b128 v[232:235], v172 offset:7168
	global_load_lds_dwordx4 v154, s[20:21]
	s_add_i32 m0, s49, 0xe000
	s_nop 0
	global_load_lds_dwordx4 v152, s[20:21]
	s_waitcnt vmcnt(8)
	s_waitcnt lgkmcnt(0)
	s_barrier
	s_setprio 1
	v_mfma_f32_16x16x32_bf16 v[132:135], v[48:51], v[190:193], v[132:135]
	v_mfma_f32_16x16x32_bf16 v[124:127], v[136:139], v[190:193], v[124:127]
	v_mfma_f32_16x16x32_bf16 v[116:119], v[48:51], v[198:201], v[116:119]
	v_mfma_f32_16x16x32_bf16 v[112:115], v[136:139], v[198:201], v[112:115]
	v_mfma_f32_16x16x32_bf16 v[100:103], v[48:51], v[206:209], v[100:103]
	v_mfma_f32_16x16x32_bf16 v[96:99], v[136:139], v[206:209], v[96:99]
	v_mfma_f32_16x16x32_bf16 v[84:87], v[48:51], v[228:231], v[84:87]
	v_mfma_f32_16x16x32_bf16 v[80:83], v[136:139], v[228:231], v[80:83]
	v_mfma_f32_16x16x32_bf16 v[132:135], v[56:59], v[194:197], v[132:135]
	v_mfma_f32_16x16x32_bf16 v[124:127], v[140:143], v[194:197], v[124:127]
	v_mfma_f32_16x16x32_bf16 v[116:119], v[56:59], v[202:205], v[116:119]
	v_mfma_f32_16x16x32_bf16 v[112:115], v[140:143], v[202:205], v[112:115]
	v_mfma_f32_16x16x32_bf16 v[100:103], v[56:59], v[210:213], v[100:103]
	v_mfma_f32_16x16x32_bf16 v[96:99], v[140:143], v[210:213], v[96:99]
	v_mfma_f32_16x16x32_bf16 v[84:87], v[56:59], v[232:235], v[84:87]
	v_mfma_f32_16x16x32_bf16 v[80:83], v[140:143], v[232:235], v[80:83]
	v_mfma_f32_16x16x32_bf16 v[128:131], v[156:159], v[190:193], v[128:131]
	v_mfma_f32_16x16x32_bf16 v[120:123], v[182:185], v[190:193], v[120:123]
	v_mfma_f32_16x16x32_bf16 v[108:111], v[156:159], v[198:201], v[108:111]
	v_mfma_f32_16x16x32_bf16 v[104:107], v[182:185], v[198:201], v[104:107]
	v_mfma_f32_16x16x32_bf16 v[92:95], v[156:159], v[206:209], v[92:95]
	v_mfma_f32_16x16x32_bf16 v[88:91], v[182:185], v[206:209], v[88:91]
	v_mfma_f32_16x16x32_bf16 v[76:79], v[156:159], v[228:231], v[76:79]
	v_mfma_f32_16x16x32_bf16 v[72:75], v[182:185], v[228:231], v[72:75]
	v_mfma_f32_16x16x32_bf16 v[128:131], v[160:163], v[194:197], v[128:131]
	v_mfma_f32_16x16x32_bf16 v[120:123], v[186:189], v[194:197], v[120:123]
	v_mfma_f32_16x16x32_bf16 v[108:111], v[160:163], v[202:205], v[108:111]
	v_mfma_f32_16x16x32_bf16 v[104:107], v[186:189], v[202:205], v[104:107]
	s_setprio 2
	s_barrier
	v_mfma_f32_16x16x32_bf16 v[92:95], v[160:163], v[210:213], v[92:95]
	v_mfma_f32_16x16x32_bf16 v[88:91], v[186:189], v[210:213], v[88:91]
	v_mfma_f32_16x16x32_bf16 v[76:79], v[160:163], v[232:235], v[76:79]
	v_mfma_f32_16x16x32_bf16 v[72:75], v[186:189], v[232:235], v[72:75]
	s_setprio 0
	s_add_i32 s64, s64, s41
	s_add_u32 s94, s22, s34
	s_addc_u32 s95, s23, s35
	s_mov_b32 m0, s64
	ds_read_b128 v[190:193], v172 offset:16384
	ds_read_b128 v[194:197], v172 offset:17408
	ds_read_b128 v[198:201], v172 offset:18432
	ds_read_b128 v[202:205], v172 offset:19456
	ds_read_b128 v[206:209], v172 offset:20480
	ds_read_b128 v[210:213], v172 offset:21504
	ds_read_b128 v[228:231], v172 offset:22528
	ds_read_b128 v[232:235], v172 offset:23552
	global_load_lds_dwordx4 v148, s[22:23]
	s_add_i32 m0, s64, 0x2000
	s_add_u32 s64, s22, 0x40000
	s_addc_u32 s65, s23, 0
	s_add_i32 s69, s69, s41
	global_load_lds_dwordx4 v144, s[22:23]
	s_mov_b32 m0, s69
	s_nop 0
	global_load_lds_dwordx4 v148, s[64:65]
	s_add_i32 m0, s69, 0x2000
	s_nop 0
	global_load_lds_dwordx4 v144, s[64:65]
	s_add_u32 s98, s24, s34
	s_addc_u32 s99, s25, s35
	s_mov_b32 m0, s49
	s_nop 0
	global_load_lds_dwordx4 v150, s[24:25]
	s_mov_b32 m0, s50
	s_nop 0
	global_load_lds_dwordx4 v146, s[24:25]
	s_waitcnt vmcnt(8)
	s_waitcnt lgkmcnt(0)
	s_barrier
	s_setprio 1
	v_mfma_f32_16x16x32_bf16 v[68:71], v[48:51], v[190:193], v[68:71]
	v_mfma_f32_16x16x32_bf16 v[64:67], v[136:139], v[190:193], v[64:67]
	v_mfma_f32_16x16x32_bf16 v[44:47], v[48:51], v[198:201], v[44:47]
	v_mfma_f32_16x16x32_bf16 v[40:43], v[136:139], v[198:201], v[40:43]
	v_mfma_f32_16x16x32_bf16 v[28:31], v[48:51], v[206:209], v[28:31]
	v_mfma_f32_16x16x32_bf16 v[24:27], v[136:139], v[206:209], v[24:27]
	v_mfma_f32_16x16x32_bf16 v[12:15], v[48:51], v[228:231], v[12:15]
	v_mfma_f32_16x16x32_bf16 v[8:11], v[136:139], v[228:231], v[8:11]
	v_mfma_f32_16x16x32_bf16 v[68:71], v[56:59], v[194:197], v[68:71]
	v_mfma_f32_16x16x32_bf16 v[64:67], v[140:143], v[194:197], v[64:67]
	v_mfma_f32_16x16x32_bf16 v[44:47], v[56:59], v[202:205], v[44:47]
	v_mfma_f32_16x16x32_bf16 v[40:43], v[140:143], v[202:205], v[40:43]
	v_mfma_f32_16x16x32_bf16 v[28:31], v[56:59], v[210:213], v[28:31]
	v_mfma_f32_16x16x32_bf16 v[24:27], v[140:143], v[210:213], v[24:27]
	v_mfma_f32_16x16x32_bf16 v[12:15], v[56:59], v[232:235], v[12:15]
	v_mfma_f32_16x16x32_bf16 v[8:11], v[140:143], v[232:235], v[8:11]
	v_mfma_f32_16x16x32_bf16 v[52:55], v[182:185], v[190:193], v[52:55]
	v_mfma_f32_16x16x32_bf16 v[36:39], v[156:159], v[198:201], v[36:39]
	v_mfma_f32_16x16x32_bf16 v[32:35], v[182:185], v[198:201], v[32:35]
	v_mfma_f32_16x16x32_bf16 v[20:23], v[156:159], v[206:209], v[20:23]
	v_mfma_f32_16x16x32_bf16 v[16:19], v[182:185], v[206:209], v[16:19]
	v_mfma_f32_16x16x32_bf16 v[4:7], v[156:159], v[228:231], v[4:7]
	v_mfma_f32_16x16x32_bf16 v[0:3], v[182:185], v[228:231], v[0:3]
	v_mfma_f32_16x16x32_bf16 v[48:51], v[156:159], v[190:193], v[60:63]
	v_mfma_f32_16x16x32_bf16 v[52:55], v[186:189], v[194:197], v[52:55]
	v_mfma_f32_16x16x32_bf16 v[36:39], v[160:163], v[202:205], v[36:39]
	v_mfma_f32_16x16x32_bf16 v[32:35], v[186:189], v[202:205], v[32:35]
	v_mfma_f32_16x16x32_bf16 v[20:23], v[160:163], v[210:213], v[20:23]
	s_setprio 2
	s_barrier
	v_mfma_f32_16x16x32_bf16 v[16:19], v[186:189], v[210:213], v[16:19]
	v_mfma_f32_16x16x32_bf16 v[4:7], v[160:163], v[232:235], v[4:7]
	v_mfma_f32_16x16x32_bf16 v[0:3], v[186:189], v[232:235], v[0:3]
	v_mfma_f32_16x16x32_bf16 v[48:51], v[160:163], v[194:197], v[48:51]
	s_setprio 0
	s_add_i32 s64, 0, 0x18000
	s_add_i32 s65, 0, 0x1c000
	v_add_u32_e32 v140, s64, v167
	v_add_u32_e32 v173, s65, v167
	ds_read_b128 v[56:59], v140
	ds_read_b128 v[60:63], v140 offset:1024
	ds_read_b128 v[136:139], v140 offset:2048
	ds_read_b128 v[140:143], v140 offset:3072
	ds_read_b128 v[156:159], v173
	ds_read_b128 v[160:163], v173 offset:1024
	ds_read_b128 v[182:185], v173 offset:2048
	ds_read_b128 v[186:189], v173 offset:3072
	s_add_u32 s24, s24, 0x40000
	s_addc_u32 s25, s25, 0
	s_mov_b32 m0, s51
	ds_read_b128 v[190:193], v172 offset:32768
	ds_read_b128 v[194:197], v172 offset:33792
	ds_read_b128 v[198:201], v172 offset:34816
	ds_read_b128 v[202:205], v172 offset:35840
	ds_read_b128 v[206:209], v172 offset:36864
	ds_read_b128 v[210:213], v172 offset:37888
	ds_read_b128 v[228:231], v172 offset:38912
	ds_read_b128 v[232:235], v172 offset:39936
	global_load_lds_dwordx4 v150, s[24:25]
	s_mov_b32 m0, s52
	s_nop 0
	global_load_lds_dwordx4 v146, s[24:25]
	s_waitcnt vmcnt(8)
	s_waitcnt lgkmcnt(0)
	s_barrier
	s_setprio 1
	v_mfma_f32_16x16x32_bf16 v[132:135], v[56:59], v[190:193], v[132:135]
	v_mfma_f32_16x16x32_bf16 v[124:127], v[136:139], v[190:193], v[124:127]
	v_mfma_f32_16x16x32_bf16 v[116:119], v[56:59], v[198:201], v[116:119]
	v_mfma_f32_16x16x32_bf16 v[112:115], v[136:139], v[198:201], v[112:115]
	v_mfma_f32_16x16x32_bf16 v[100:103], v[56:59], v[206:209], v[100:103]
	v_mfma_f32_16x16x32_bf16 v[96:99], v[136:139], v[206:209], v[96:99]
	v_mfma_f32_16x16x32_bf16 v[84:87], v[56:59], v[228:231], v[84:87]
	v_mfma_f32_16x16x32_bf16 v[80:83], v[136:139], v[228:231], v[80:83]
	v_mfma_f32_16x16x32_bf16 v[132:135], v[60:63], v[194:197], v[132:135]
	v_mfma_f32_16x16x32_bf16 v[124:127], v[140:143], v[194:197], v[124:127]
	v_mfma_f32_16x16x32_bf16 v[116:119], v[60:63], v[202:205], v[116:119]
	v_mfma_f32_16x16x32_bf16 v[112:115], v[140:143], v[202:205], v[112:115]
	v_mfma_f32_16x16x32_bf16 v[100:103], v[60:63], v[210:213], v[100:103]
	v_mfma_f32_16x16x32_bf16 v[96:99], v[140:143], v[210:213], v[96:99]
	v_mfma_f32_16x16x32_bf16 v[84:87], v[60:63], v[232:235], v[84:87]
	v_mfma_f32_16x16x32_bf16 v[80:83], v[140:143], v[232:235], v[80:83]
	v_mfma_f32_16x16x32_bf16 v[128:131], v[156:159], v[190:193], v[128:131]
	v_mfma_f32_16x16x32_bf16 v[120:123], v[182:185], v[190:193], v[120:123]
	v_mfma_f32_16x16x32_bf16 v[108:111], v[156:159], v[198:201], v[108:111]
	v_mfma_f32_16x16x32_bf16 v[104:107], v[182:185], v[198:201], v[104:107]
	v_mfma_f32_16x16x32_bf16 v[92:95], v[156:159], v[206:209], v[92:95]
	v_mfma_f32_16x16x32_bf16 v[88:91], v[182:185], v[206:209], v[88:91]
	v_mfma_f32_16x16x32_bf16 v[76:79], v[156:159], v[228:231], v[76:79]
	v_mfma_f32_16x16x32_bf16 v[72:75], v[182:185], v[228:231], v[72:75]
	v_mfma_f32_16x16x32_bf16 v[128:131], v[160:163], v[194:197], v[128:131]
	v_mfma_f32_16x16x32_bf16 v[120:123], v[186:189], v[194:197], v[120:123]
	v_mfma_f32_16x16x32_bf16 v[108:111], v[160:163], v[202:205], v[108:111]
	v_mfma_f32_16x16x32_bf16 v[104:107], v[186:189], v[202:205], v[104:107]
	s_setprio 2
	s_barrier
	v_mfma_f32_16x16x32_bf16 v[92:95], v[160:163], v[210:213], v[92:95]
	v_mfma_f32_16x16x32_bf16 v[88:91], v[186:189], v[210:213], v[88:91]
	v_mfma_f32_16x16x32_bf16 v[76:79], v[160:163], v[232:235], v[76:79]
	v_mfma_f32_16x16x32_bf16 v[72:75], v[186:189], v[232:235], v[72:75]
	s_setprio 0
	s_add_i32 s24, s64, s41
	s_mov_b32 m0, s24
	ds_read_b128 v[190:193], v172 offset:49152
	ds_read_b128 v[194:197], v172 offset:50176
	ds_read_b128 v[198:201], v172 offset:51200
	ds_read_b128 v[202:205], v172 offset:52224
	ds_read_b128 v[206:209], v172 offset:53248
	ds_read_b128 v[210:213], v172 offset:54272
	ds_read_b128 v[228:231], v172 offset:55296
	ds_read_b128 v[232:235], v172 offset:56320
	global_load_lds_dwordx4 v148, s[94:95]
	s_add_i32 m0, s24, 0x2000
	s_add_u32 s22, s22, 0x40080
	s_addc_u32 s23, s23, 0
	s_add_i32 s24, s65, s41
	global_load_lds_dwordx4 v144, s[94:95]
	s_mov_b32 m0, s24
	s_nop 0
	global_load_lds_dwordx4 v148, s[22:23]
	s_add_i32 m0, s24, 0x2000
	s_nop 0
	global_load_lds_dwordx4 v144, s[22:23]
	s_mov_b32 m0, s55
	s_nop 0
	global_load_lds_dwordx4 v150, s[98:99]
	s_mov_b32 m0, s56
	s_nop 0
	global_load_lds_dwordx4 v146, s[98:99]
	s_waitcnt vmcnt(8)
	s_waitcnt lgkmcnt(0)
	s_barrier
	s_setprio 1
	v_mfma_f32_16x16x32_bf16 v[68:71], v[56:59], v[190:193], v[68:71]
	v_mfma_f32_16x16x32_bf16 v[64:67], v[136:139], v[190:193], v[64:67]
	v_mfma_f32_16x16x32_bf16 v[44:47], v[56:59], v[198:201], v[44:47]
	v_mfma_f32_16x16x32_bf16 v[40:43], v[136:139], v[198:201], v[40:43]
	v_mfma_f32_16x16x32_bf16 v[28:31], v[56:59], v[206:209], v[28:31]
	v_mfma_f32_16x16x32_bf16 v[24:27], v[136:139], v[206:209], v[24:27]
	v_mfma_f32_16x16x32_bf16 v[12:15], v[56:59], v[228:231], v[12:15]
	v_mfma_f32_16x16x32_bf16 v[8:11], v[136:139], v[228:231], v[8:11]
	v_mfma_f32_16x16x32_bf16 v[68:71], v[60:63], v[194:197], v[68:71]
	v_mfma_f32_16x16x32_bf16 v[64:67], v[140:143], v[194:197], v[64:67]
	v_mfma_f32_16x16x32_bf16 v[44:47], v[60:63], v[202:205], v[44:47]
	v_mfma_f32_16x16x32_bf16 v[40:43], v[140:143], v[202:205], v[40:43]
	v_mfma_f32_16x16x32_bf16 v[28:31], v[60:63], v[210:213], v[28:31]
	v_mfma_f32_16x16x32_bf16 v[24:27], v[140:143], v[210:213], v[24:27]
	v_mfma_f32_16x16x32_bf16 v[12:15], v[60:63], v[232:235], v[12:15]
	v_mfma_f32_16x16x32_bf16 v[8:11], v[140:143], v[232:235], v[8:11]
	v_mfma_f32_16x16x32_bf16 v[48:51], v[156:159], v[190:193], v[48:51]
	v_mfma_f32_16x16x32_bf16 v[60:63], v[160:163], v[194:197], v[48:51]
	v_mfma_f32_16x16x32_bf16 v[48:51], v[182:185], v[190:193], v[52:55]
	v_mfma_f32_16x16x32_bf16 v[36:39], v[156:159], v[198:201], v[36:39]
	v_mfma_f32_16x16x32_bf16 v[32:35], v[182:185], v[198:201], v[32:35]
	v_mfma_f32_16x16x32_bf16 v[20:23], v[156:159], v[206:209], v[20:23]
	v_mfma_f32_16x16x32_bf16 v[16:19], v[182:185], v[206:209], v[16:19]
	v_mfma_f32_16x16x32_bf16 v[4:7], v[156:159], v[228:231], v[4:7]
	v_mfma_f32_16x16x32_bf16 v[0:3], v[182:185], v[228:231], v[0:3]
	v_mfma_f32_16x16x32_bf16 v[52:55], v[186:189], v[194:197], v[48:51]
	v_mfma_f32_16x16x32_bf16 v[36:39], v[160:163], v[202:205], v[36:39]
	v_mfma_f32_16x16x32_bf16 v[32:35], v[186:189], v[202:205], v[32:35]
	s_setprio 2
	s_barrier
	v_mfma_f32_16x16x32_bf16 v[20:23], v[160:163], v[210:213], v[20:23]
	v_mfma_f32_16x16x32_bf16 v[16:19], v[186:189], v[210:213], v[16:19]
	v_mfma_f32_16x16x32_bf16 v[4:7], v[160:163], v[232:235], v[4:7]
	v_mfma_f32_16x16x32_bf16 v[0:3], v[186:189], v[232:235], v[0:3]
	s_setprio 0
	s_add_i32 s68, s68, 2
	s_add_u32 s62, s62, 0x100
	s_addc_u32 s63, s63, 0
	s_add_u32 s20, s20, 0x100
	s_addc_u32 s21, s21, 0
	s_cmp_gt_u32 s68, 13
	s_cbranch_scc0 .LBB0_252
	s_and_b64 vcc, exec, s[8:9]
	s_cbranch_vccz .LBB0_255
	s_barrier
